# v41: v33 + two p0 exps moved from the PV1 gap to the PV3 gap in half 1 + conv pool flat_store_short converted to global_store_short
# speedup vs baseline: 1.0005x; 1.0005x over previous
; __device__ __forceinline__ void convpool_phase(const Params& p, int l, LAS float* hb) {
;     ...
;         { const int tt0 = half * 16; float sum = 0.f;
; #pragma unroll
;           for (int k = 0; k < 16; ++k) if (k < wlen) sum += pb[(tt0 + 8 - left + k) * 256 + c];
; #pragma unroll 4
;           for (int q = 0; q < 16; ++q) { const int tt = tt0 + q, t = t0 + tt;
;               const int lo = max(t - left, s0), hi = min(t + wlen - left, s1);
;               const float d = sum / (float)(hi - lo) - pb[(tt + 8) * 256 + c];
;               CAT[(size_t)t * LDC + 256 + c] = (f16)d;
;               sum += pb[(tt + 8 - left + wlen) * 256 + c] - pb[(tt + 8 - left) * 256 + c]; } }
.LBB0_486:
	v_add_u32_e32 v20, s0, v124
	v_add_u32_e32 v21, s0, v123
	v_max_i32_e32 v11, s20, v20
	v_min_i32_e32 v14, s21, v21
	v_sub_u32_e32 v11, v14, v11
	v_cvt_f32_i32_e32 v11, v11
	v_add_u32_e32 v10, s0, v122
	v_add_u32_e32 v22, v12, v126
	s_add_i32 s0, s0, 4
	v_div_scale_f32 v14, s[2:3], v11, v11, v13
	v_rcp_f32_e32 v15, v14
	s_cmp_lg_u32 s0, 16
	v_fma_f32 v16, -v14, v15, 1.0
	v_fmac_f32_e32 v15, v16, v15
	v_div_scale_f32 v16, vcc, v13, v11, v13
	v_mul_f32_e32 v17, v16, v15
	v_fma_f32 v18, -v14, v17, v16
	v_fmac_f32_e32 v17, v18, v15
	v_fma_f32 v14, -v14, v17, v16
	v_div_fmas_f32 v14, v14, v15, v17
	v_div_fixup_f32 v11, v14, v11, v13
	ds_read2st64_b32 v[14:15], v12 offset1:4
	ds_read2st64_b32 v[18:19], v22 offset1:4
	s_waitcnt lgkmcnt(0)
	v_sub_f32_e32 v11, v11, v14
	v_cvt_f16_f32_e32 v14, v11
	v_ashrrev_i32_e32 v11, 31, v10
	v_lshlrev_b64 v[16:17], 11, v[10:11]
	v_lshl_add_u64 v[16:17], v[58:59], 0, v[16:17]
	v_add_u32_e32 v11, v12, v127
	global_store_short v[16:17], v14, off offset:512
	ds_read2st64_b32 v[16:17], v11 offset1:4
	s_waitcnt lgkmcnt(0)
	v_sub_f32_e32 v14, v16, v18
	v_add_u32_e32 v16, 1, v20
	v_add_u32_e32 v18, 1, v21
	v_max_i32_e32 v16, s20, v16
	v_min_i32_e32 v18, s21, v18
	v_sub_u32_e32 v16, v18, v16
	v_cvt_f32_i32_e32 v16, v16
	v_add_f32_e32 v13, v13, v14
	v_add_u32_e32 v14, 1, v10
	v_div_scale_f32 v18, s[2:3], v16, v16, v13
	v_rcp_f32_e32 v23, v18
	s_nop 0
	v_fma_f32 v24, -v18, v23, 1.0
	v_fmac_f32_e32 v23, v24, v23
	v_div_scale_f32 v24, vcc, v13, v16, v13
	v_mul_f32_e32 v25, v24, v23
	v_fma_f32 v26, -v18, v25, v24
	v_fmac_f32_e32 v25, v26, v23
	v_fma_f32 v18, -v18, v25, v24
	v_div_fmas_f32 v18, v18, v23, v25
	v_div_fixup_f32 v16, v18, v16, v13
	v_sub_f32_e32 v15, v16, v15
	v_cvt_f16_f32_e32 v16, v15
	v_ashrrev_i32_e32 v15, 31, v14
	v_lshlrev_b64 v[14:15], 11, v[14:15]
	v_lshl_add_u64 v[14:15], v[58:59], 0, v[14:15]
	global_store_short v[14:15], v16, off offset:512
	v_add_u32_e32 v15, 2, v20
	v_add_u32_e32 v16, 2, v21
	v_max_i32_e32 v15, s20, v15
	v_min_i32_e32 v16, s21, v16
	v_sub_u32_e32 v15, v16, v15
	v_cvt_f32_i32_e32 v15, v15
	v_sub_f32_e32 v14, v17, v19
	v_add_f32_e32 v13, v13, v14
	v_add_u32_e32 v14, 2, v10
	v_div_scale_f32 v16, s[2:3], v15, v15, v13
	v_rcp_f32_e32 v17, v16
	v_add_u32_e32 v10, 3, v10
	v_fma_f32 v18, -v16, v17, 1.0
	v_fmac_f32_e32 v17, v18, v17
	v_div_scale_f32 v18, vcc, v13, v15, v13
	v_mul_f32_e32 v19, v18, v17
	v_fma_f32 v23, -v16, v19, v18
	v_fmac_f32_e32 v19, v23, v17
	v_fma_f32 v16, -v16, v19, v18
	v_div_fmas_f32 v16, v16, v17, v19
	v_div_fixup_f32 v15, v16, v15, v13
	ds_read2st64_b32 v[16:17], v12 offset0:8 offset1:12
	v_add_u32_e32 v12, 0x1000, v12
	s_waitcnt lgkmcnt(0)
	v_sub_f32_e32 v15, v15, v16
	v_cvt_f16_f32_e32 v16, v15
	v_ashrrev_i32_e32 v15, 31, v14
	v_lshlrev_b64 v[14:15], 11, v[14:15]
	v_lshl_add_u64 v[14:15], v[58:59], 0, v[14:15]
	global_store_short v[14:15], v16, off offset:512
	ds_read2st64_b32 v[14:15], v11 offset0:8 offset1:12
	ds_read2st64_b32 v[18:19], v22 offset0:8 offset1:12
	s_waitcnt lgkmcnt(0)
	v_sub_f32_e32 v11, v14, v18
	v_add_f32_e32 v13, v13, v11
	v_add_u32_e32 v11, 3, v20
	v_add_u32_e32 v14, 3, v21
	v_max_i32_e32 v11, s20, v11
	v_min_i32_e32 v14, s21, v14
	v_sub_u32_e32 v11, v14, v11
	v_cvt_f32_i32_e32 v11, v11
	v_div_scale_f32 v14, s[2:3], v11, v11, v13
	v_rcp_f32_e32 v16, v14
	s_nop 0
	v_fma_f32 v18, -v14, v16, 1.0
	v_fmac_f32_e32 v16, v18, v16
	v_div_scale_f32 v18, vcc, v13, v11, v13
	v_mul_f32_e32 v20, v18, v16
	v_fma_f32 v21, -v14, v20, v18
	v_fmac_f32_e32 v20, v21, v16
	v_fma_f32 v14, -v14, v20, v18
	v_div_fmas_f32 v14, v14, v16, v20
	v_div_fixup_f32 v11, v14, v11, v13
	v_sub_f32_e32 v11, v11, v17
	v_cvt_f16_f32_e32 v14, v11
	v_ashrrev_i32_e32 v11, 31, v10
	v_lshlrev_b64 v[10:11], 11, v[10:11]
	v_lshl_add_u64 v[10:11], v[58:59], 0, v[10:11]
	global_store_short v[10:11], v14, off offset:512
	v_sub_f32_e32 v10, v15, v19
	v_add_f32_e32 v13, v13, v10
	s_cbranch_scc1 .LBB0_486
	s_mov_b32 s2, 0
	s_mov_b64 s[0:1], -1

; #define LAS __attribute__((address_space(3)))
; template <bool FIRST>
; __device__ __forceinline__ void partialSM(f32x16& p0, f32x16& p1, f32x16& negm, float& dl, float& alpha) {
;     float pmax = p0[0];
; #pragma unroll
;     for (int r = 1; r < 16; ++r) pmax = fmaxf(pmax, p0[r]);
; #pragma unroll
;     for (int r = 0; r < 16; ++r) pmax = fmaxf(pmax, p1[r]);
;     { auto rr = __builtin_amdgcn_permlane32_swap(__float_as_uint(pmax), __float_as_uint(pmax), false, false);
;       pmax = fmaxf(__uint_as_float(rr[0]), __uint_as_float(rr[1])); }
;     if (FIRST) {
;         dl = 0.f; alpha = 1.f; const float d0_ = pmax - SH;
; #pragma unroll
;         for (int r = 0; r < 16; ++r) { p0[r] -= d0_; p1[r] -= d0_; negm[r] -= d0_; }
;     } else {
;         const bool keep = __all(pmax <= SH + THRL);
;         dl = keep ? 0.f : fmaxf(pmax - SH, 0.f); alpha = __builtin_amdgcn_exp2f(-dl);
;     }
; #pragma unroll
;     for (int r = 0; r < 16; ++r) p0[r] = __builtin_amdgcn_exp2f(p0[r]);
; }
; __device__ __forceinline__ void finishSM(f32x16& p0, f32x16& p1, v8i& pa) {
; #pragma unroll
;     for (int r = 0; r < 16; ++r) p1[r] = __builtin_amdgcn_exp2f(p1[r]);
; #pragma unroll
;     for (int w = 0; w < 4; ++w) { pa[w] = (int)pk4_fp8(p0[4 * w], p0[4 * w + 1], p0[4 * w + 2], p0[4 * w + 3]); pa[4 + w] = (int)pk4_fp8(p1[4 * w], p1[4 * w + 1], p1[4 * w + 2], p1[4 * w + 3]); }
; }
; __device__ __forceinline__ v8i ld32(const LAS char* a0, const LAS char* a1) { const v4i x = *(const LAS v4i*)a0, y = *(const LAS v4i*)a1; return (v8i){x[0], x[1], x[2], x[3], y[0], y[1], y[2], y[3]}; }
; __device__ __forceinline__ void qkt(f32x16& p0, f32x16& p1, const LAS char* Ks, int ka0, int ka1, const v8i* qf, const f32x16& negm) {
; #pragma unroll
;     for (int st = 0; st < 3; ++st) {
;         const v8i k0 = ld32(Ks + ka0 + 64 * st, Ks + ka1 + 64 * st), k1 = ld32(Ks + ka0 + 64 * st + 32 * 192, Ks + ka1 + 64 * st + 32 * 192);
;         if (st == 0) { p0 = MFMA8QK(k0, qf[st], negm); p1 = MFMA8QK(k1, qf[st], negm); }
;         else { p0 = MFMA8QK(k0, qf[st], p0); p1 = MFMA8QK(k1, qf[st], p1); } }
; }
; __device__ __forceinline__ void pv_d0(f32x16* o, const LAS char* Vs, int va0, int va1, v8i pa) {
; #pragma unroll
;     for (int d0 = 0; d0 < 4; ++d0) { const v8i vf = ld32(Vs + va0 + 2048 * d0, Vs + va1 + 2048 * d0); o[d0] = MFMA8(pa, vf, o[d0]); }
.LBB0_589:
	s_bitcmp1_b32 s15, 0
	s_cselect_b32 s0, 0x6000, 0
	s_add_i32 s0, s0, 0
	v_add_u32_e32 v0, s0, v244
	v_add_u32_e32 v210, s0, v245
	v_add_u32_e32 v211, 0xf000, v0
	v_add_u32_e32 v212, 0xf000, v210
	ds_read_b128 v[2:5], v0 offset:61504
	ds_read_b128 v[6:9], v210 offset:61504
	v_exp_f32_e32 v14, v116
	v_exp_f32_e32 v15, v117
	v_exp_f32_e32 v12, v114
	v_exp_f32_e32 v13, v115
	s_waitcnt lgkmcnt(4)
	v_mfma_scale_f32_32x32x64_f8f6f4 v[144:159], v[202:209], v[184:191], v[96:111], v234, v233 op_sel_hi:[0,0,0]
	ds_read_b128 v[202:205], v211 offset:6208
	ds_read_b128 v[206:209], v212 offset:6208
	v_exp_f32_e32 v114, v118
	v_exp_f32_e32 v115, v119
	v_exp_f32_e32 v119, v120
	v_exp_f32_e32 v120, v121
	v_cvt_pk_fp8_f32 v117, v14, v15
	v_exp_f32_e32 v10, v112
	v_exp_f32_e32 v11, v113
	s_waitcnt lgkmcnt(4)
	v_mfma_scale_f32_32x32x64_f8f6f4 v[128:143], v[194:201], v[184:191], v[96:111], v234, v233 op_sel_hi:[0,0,0]
	ds_read_b128 v[194:197], v0 offset:61568
	ds_read_b128 v[198:201], v210 offset:61568
	v_exp_f32_e32 v121, v122
	v_exp_f32_e32 v122, v123
	v_exp_f32_e32 v123, v124
	v_exp_f32_e32 v124, v125
	v_cvt_pk_fp8_f32 v117, v114, v115 op_sel:[0,0,1]
	v_cvt_pk_fp8_f32 v118, v119, v120
	v_exp_f32_e32 v125, v126
	s_waitcnt lgkmcnt(4)
	v_mfma_scale_f32_32x32x64_f8f6f4 v[144:159], v[2:9], v[176:183], v[144:159], v234, v233 op_sel_hi:[0,0,0]
	ds_read_b128 v[2:5], v211 offset:6272
	ds_read_b128 v[6:9], v212 offset:6272
	v_exp_f32_e32 v126, v127
	v_cvt_pk_fp8_f32 v112, v228, v229
	v_cvt_pk_fp8_f32 v116, v10, v11
	v_cvt_pk_fp8_f32 v113, v226, v227
	v_cvt_pk_fp8_f32 v114, v222, v223
	v_cvt_pk_fp8_f32 v115, v166, v167
	s_waitcnt lgkmcnt(4)
	v_mfma_scale_f32_32x32x64_f8f6f4 v[128:143], v[202:209], v[176:183], v[128:143], v234, v233 op_sel_hi:[0,0,0]
	v_cvt_pk_fp8_f32 v119, v123, v124
	v_cvt_pk_fp8_f32 v112, v220, v221 op_sel:[0,0,1]
	v_cvt_pk_fp8_f32 v116, v12, v13 op_sel:[0,0,1]
	v_cvt_pk_fp8_f32 v113, v224, v225 op_sel:[0,0,1]
	v_cvt_pk_fp8_f32 v114, v162, v163 op_sel:[0,0,1]
	v_cvt_pk_fp8_f32 v118, v121, v122 op_sel:[0,0,1]
	s_waitcnt lgkmcnt(2)
	v_mfma_scale_f32_32x32x64_f8f6f4 v[144:159], v[194:201], v[168:175], v[144:159], v234, v233 op_sel_hi:[0,0,0]
	v_cvt_pk_fp8_f32 v115, v164, v165 op_sel:[0,0,1]
	v_cvt_pk_fp8_f32 v119, v125, v126 op_sel:[0,0,1]
	v_mov_b32_e32 v161, v160
	v_mov_b32_e32 v162, v160
	v_mov_b32_e32 v163, v160
	s_waitcnt lgkmcnt(0)
	v_mfma_scale_f32_32x32x64_f8f6f4 v[128:143], v[2:9], v[168:175], v[128:143], v234, v233 op_sel_hi:[0,0,0]
	v_mov_b32_e32 v164, v160
	v_mov_b32_e32 v165, v160
	v_mov_b32_e32 v166, v160
	v_mov_b32_e32 v167, v160
	s_add_i32 s66, s21, -2
	s_ashr_i32 s38, s66, 1
	s_mul_hi_i32 s0, s38, 0x55555556
	s_lshr_b32 s1, s0, 31
	s_add_i32 s0, s0, s1
	s_mul_i32 s0, s0, 3
	s_sub_i32 s0, s38, s0
	s_lshl_b32 s0, s0, 14
	s_add_i32 s0, s0, 0
	v_add_u32_e32 v0, s0, v241
	v_add_u32_e32 v11, s0, v240
	ds_read_b128 v[208:211], v0
	ds_read_b128 v[212:215], v11
	ds_read_b128 v[200:203], v0 offset:2048
	ds_read_b128 v[204:207], v11 offset:2048
	ds_read_b128 v[192:195], v0 offset:4096
	ds_read_b128 v[196:199], v11 offset:4096
	ds_read_b128 v[2:5], v0 offset:6144
	ds_read_b128 v[6:9], v11 offset:6144
	v_mov_b32_e32 v125, 0x19000
	v_lshl_add_u32 v126, v216, 4, v125
	v_lshl_add_u32 v127, v216, 2, v125
	ds_read_b128 v[120:123], v126
	ds_read_b32 v124, v127 offset:8192
	v_max_f32_e32 v0, v144, v145
	v_max3_f32 v0, v0, v146, v147
	v_max3_f32 v0, v0, v148, v149
	v_max3_f32 v0, v0, v150, v151
	v_max3_f32 v0, v0, v152, v153
	v_max3_f32 v0, v0, v154, v155
	v_max3_f32 v0, v0, v156, v157
	v_max3_f32 v0, v0, v158, v159
	s_waitcnt lgkmcnt(8)
	v_mfma_scale_f32_32x32x64_f8f6f4 v[64:79], v[112:119], v[208:215], v[64:79], v234, v234 op_sel_hi:[0,0,0]
	v_exp_f32_e32 v14, v144
	v_exp_f32_e32 v15, v145
	v_max3_f32 v0, v0, v128, v129
	v_max3_f32 v0, v0, v130, v131
	v_max3_f32 v0, v0, v132, v133
	v_max3_f32 v0, v0, v134, v135
	s_waitcnt lgkmcnt(6)
	v_mfma_scale_f32_32x32x64_f8f6f4 v[48:63], v[112:119], v[200:207], v[48:63], v234, v234 op_sel_hi:[0,0,0]
	v_exp_f32_e32 v12, v150
	v_exp_f32_e32 v13, v151
	v_max3_f32 v0, v0, v136, v137
	v_max3_f32 v0, v0, v138, v139
	v_max3_f32 v0, v0, v140, v141
	v_max3_f32 v0, v0, v142, v143
	s_waitcnt lgkmcnt(4)
	v_mfma_scale_f32_32x32x64_f8f6f4 v[32:47], v[112:119], v[192:199], v[32:47], v234, v234 op_sel_hi:[0,0,0]
	v_exp_f32_e32 v192, v146
	v_exp_f32_e32 v193, v147
	v_exp_f32_e32 v10, v148
	v_exp_f32_e32 v11, v149
	v_mov_b32_e32 v125, v0
	s_nop 1
	v_permlane32_swap_b32_e32 v0, v125
	s_waitcnt lgkmcnt(2)
	v_mfma_scale_f32_32x32x64_f8f6f4 v[16:31], v[112:119], v[2:9], v[16:31], v234, v234 op_sel_hi:[0,0,0]
	v_exp_f32_e32 v6, v152
	v_exp_f32_e32 v7, v153
	v_exp_f32_e32 v8, v154
	v_exp_f32_e32 v9, v155
	v_mfma_scale_f32_32x32x64_f8f6f4 v[80:95], v[112:119], v[160:167], v[80:95], v234, v234 op_sel_hi:[0,0,0]
	v_exp_f32_e32 v2, v156
	v_exp_f32_e32 v3, v157
	v_exp_f32_e32 v4, v158
	v_exp_f32_e32 v5, v159
	s_waitcnt vmcnt(0) lgkmcnt(0)
	s_barrier
	v_max_f32_e32 v0, v0, v125
	s_add_i32 s42, s38, 2
	v_cmp_ge_f32_e64 s[0:1], s67, v0
	s_cmp_ge_i32 s42, s14
	s_cbranch_scc1 .Lattn_noissue
	s_bitcmp1_b32 s21, 1
	s_cselect_b32 s44, 0x6000, 0
	v_add_u32_e32 v126, s44, v244
	v_add_u32_e32 v127, s44, v245
	ds_read_b128 v[208:211], v126 offset:49152
	ds_read_b128 v[212:215], v127 offset:49152
	s_ashr_i32 s43, s42, 31
	s_mul_i32 s38, s42, 0x18000
	s_mul_hi_i32 s39, s42, 0x18000
	s_add_u32 s38, s24, s38
	s_addc_u32 s39, s25, s39
	s_lshl_b64 s[40:41], s[42:43], 14
	s_add_u32 s40, s52, s40
	s_addc_u32 s41, s53, s41
	s_mul_hi_i32 s43, s42, 0x55555556
	s_lshr_b32 s67, s43, 31
	s_add_i32 s43, s43, s67
	s_mul_i32 s43, s43, 3
	s_sub_i32 s42, s42, s43
	s_lshl_b32 s67, s42, 14
	s_bitcmp1_b32 s66, 1
	s_mov_b32 s42, 0xa000
	s_cselect_b32 s66, 0x10000, s42
	s_and_b64 vcc, exec, s[6:7]
	s_cbranch_vccnz .Lattn_iss_hi
	s_add_i32 m0, s67, s28
	s_nop 0
	global_load_lds_dwordx4 v120, s[40:41]
	s_add_i32 m0, s2, s66
	s_nop 0
	global_load_lds_dwordx4 v121, s[38:39]
	s_add_i32 m0, s27, s66
	s_nop 0
	global_load_lds_dwordx4 v122, s[38:39]
	s_add_i32 m0, s67, s31
	s_nop 0
	global_load_lds_dwordx4 v123, s[40:41]
	s_add_i32 m0, s33, s66
	s_nop 0
	global_load_lds_dwordx4 v124, s[38:39]
	s_branch .Lattn_iss_done
